# gate|up phases: prep jobs spread over all 256 workgroups (rank=c, nblk=256) instead of upper 128
# baseline (speedup 1.0000x reference)
.LBB0_1109:
	s_cmpk_gt_i32 s55, -1
	s_cselect_b64 s[4:5], -1, 0
	s_cmpk_eq_i32 s93, 0x100
	s_cselect_b64 s[6:7], -1, 0
	s_and_b64 s[4:5], s[4:5], s[6:7]
	s_cmp_lt_u32 s85, 10
	s_cselect_b64 s[6:7], -1, 0
	s_or_b64 s[6:7], s[6:7], s[2:3]
	s_and_b64 s[4:5], s[4:5], s[6:7]
	v_readlane_b32 s6, v254, 55
	v_readlane_b32 s7, v254, 56
	s_and_b64 s[4:5], s[4:5], s[6:7]
	s_mov_b64 s[34:35], s[80:81]
	s_andn2_b64 vcc, exec, s[4:5]
	s_cbranch_vccnz .LBB0_1211
	v_mov_b32_e32 v80, v135
	s_mov_b64 s[4:5], s[0:1]
	s_add_i32 s6, s68, -12
	s_load_dwordx2 s[4:5], s[4:5], 0x88
	s_and_b64 s[2:3], s[2:3], exec
	s_cselect_b32 s2, 1, 2
	s_cmp_gt_u32 s6, 9
	s_cselect_b32 s6, s2, 4
	s_cmp_lt_i32 s6, 2
	s_cbranch_scc1 .LBB0_1118
	s_cmp_gt_i32 s6, 3
	s_mov_b64 s[2:3], -1
	s_cbranch_scc0 .LBB0_1113
	s_mov_b64 s[2:3], 0

.LBB0_1122:
	s_add_i32 s3, s78, s3
	s_add_i32 s80, s3, s15
	s_mov_b32 s79, s55
	s_add_i32 s80, s80, s42
	s_cmp_ge_u32 s79, s80
	s_cbranch_scc1 .LBB0_1211
	v_cvt_f32_i32_e32 v3, v80
	s_mov_b32 s22, 0x3fb8aa3b
	s_movk_i32 s38, 0x400
	v_cmp_gt_i32_e64 s[6:7], s38, v80
	v_mul_f32_e32 v0, 0xbe99999a, v3
	v_mul_f32_e32 v1, 0x3fb8aa3b, v0
	v_fma_f32 v2, v0, s22, -v1
	v_rndne_f32_e32 v4, v1
	v_fmac_f32_e32 v2, 0x32a5705f, v0
	v_sub_f32_e32 v1, v1, v4
	v_add_f32_e32 v1, v1, v2
	v_exp_f32_e32 v1, v1
	v_cvt_i32_f32_e32 v2, v4
	s_mov_b32 s23, 0xc2ce8ed0
	v_writelane_b32 v254, s6, 43
	v_cmp_ngt_f32_e32 vcc, s23, v0
	v_ldexp_f32 v1, v1, v2
	s_mov_b32 s24, 0x42b17218
	v_writelane_b32 v254, s7, 44
	v_cmp_gt_i32_e64 s[6:7], 2, v80
	v_cndmask_b32_e32 v1, 0, v1, vcc
	v_cmp_nlt_f32_e32 vcc, s24, v0
	v_writelane_b32 v255, s6, 3
	v_ashrrev_i32_e32 v81, 31, v80
	v_cndmask_b32_e32 v0, v209, v1, vcc
	s_waitcnt lgkmcnt(0)
	s_add_u32 s10, s4, 0x6200000
	v_writelane_b32 v255, s7, 4
	v_fmamk_f32 v128, v0, 0xbf19999a, v196
	v_lshl_add_u64 v[0:1], v[80:81], 2, s[4:5]
	s_mov_b64 s[6:7], 0x629c000
	s_addc_u32 s11, s5, 0
	s_movk_i32 s3, 0x1000
	v_lshl_add_u64 v[84:85], v[0:1], 0, s[6:7]
	v_cmp_gt_i32_e64 s[6:7], s3, v80
	s_add_u32 s12, s4, 0x6220000
	s_addc_u32 s13, s5, 0
	v_writelane_b32 v255, s6, 5
	s_movk_i32 s3, 0x800
	v_cmp_gt_i32_e64 s[8:9], s51, v80
	v_writelane_b32 v255, s7, 6
	s_add_u32 s6, s4, 0x5200000
	s_addc_u32 s7, s5, 0
	v_cmp_gt_i32_e64 s[26:27], s3, v80
	v_writelane_b32 v254, s8, 49
	s_movk_i32 s3, 0x280
	v_cmp_gt_i32_e64 s[16:17], s3, v80
	v_writelane_b32 v254, s9, 50
	s_add_u32 s8, s4, 0x5a00000
	s_addc_u32 s9, s5, 0
	v_writelane_b32 v254, s16, 57
	s_add_u32 s3, s4, 0x6240000
	v_mul_f32_e32 v3, 0x3d000000, v3
	v_writelane_b32 v254, s17, 58
	v_writelane_b32 v254, s3, 63
	s_addc_u32 s3, s5, 0
	v_writelane_b32 v255, s3, 1
	s_add_u32 s3, s4, 0x4d00000
	v_mul_f32_e64 v6, |v3|, 0.5
	v_writelane_b32 v254, s3, 55
	v_fract_f32_e32 v7, v6
	s_mov_b32 s3, 0x7f800000
	v_add_f32_e32 v7, v7, v7
	v_cmp_neq_f32_e32 vcc, s3, v6
	v_cmp_gt_f32_e64 s[18:19], |v3|, 1.0
	v_and_b32_e32 v4, 0x7fffffff, v3
	v_cndmask_b32_e32 v6, 0, v7, vcc
	v_cndmask_b32_e64 v6, |v3|, v6, s[18:19]
	v_add_f32_e32 v7, v6, v6
	v_rndne_f32_e32 v7, v7
	v_fmac_f32_e32 v6, -0.5, v7
	v_mul_f32_e32 v8, v6, v6
	v_fmamk_f32 v9, v8, 0x3e75aa41, v134
	v_fmaak_f32 v9, v8, v9, 0x40234736
	v_fmaak_f32 v9, v8, v9, 0xc0a55e0e
	v_mul_f32_e32 v10, v6, v8
	v_mul_f32_e32 v9, v10, v9
	v_cvt_i32_f32_e32 v7, v7
	v_fmac_f32_e32 v9, 0x40490fdb, v6
	v_fmamk_f32 v6, v8, 0x3d4be544, v136
	v_fmaak_f32 v6, v8, v6, 0xbfaad1da
	v_fmaak_f32 v6, v8, v6, 0x4081e0d3
	v_fmaak_f32 v6, v8, v6, 0xc09de9e6
	v_fma_f32 v6, v8, v6, 1.0
	v_and_b32_e32 v8, 1, v7
	v_lshlrev_b32_e32 v10, 30, v7
	v_cmp_eq_u32_e32 vcc, 0, v8
	v_and_b32_e32 v10, 0x80000000, v10
	v_xor_b32_e32 v4, v4, v3
	v_cndmask_b32_e32 v8, v6, v9, vcc
	v_xor_b32_e32 v4, v4, v10
	v_xor_b32_e32 v4, v4, v8
	v_cmp_class_f32_e64 s[18:19], v3, s63
	v_and_b32_e32 v3, 2, v7
	v_add_u32_e32 v88, 0x200, v80
	v_cndmask_b32_e64 v152, v207, v4, s[18:19]
	v_cndmask_b32_e64 v4, -v9, v6, vcc
	v_cmp_eq_u32_e32 vcc, 0, v3
	v_add_u32_e32 v92, 0x600, v80
	s_addc_u32 s84, s5, 0
	v_cndmask_b32_e64 v3, -v4, v4, vcc
	v_cndmask_b32_e64 v153, v207, v3, s[18:19]
	v_and_b32_e32 v3, 15, v80
	v_cvt_f32_ubyte0_e32 v3, v3
	v_mul_f32_e32 v3, 0x3d800000, v3
	v_cmp_eq_f32_e32 vcc, 0, v3
	s_mov_b32 s18, 0x3f2aaaab
	s_add_u32 s85, s4, 0x4200000
	v_cndmask_b32_e64 v16, v210, 1.0, vcc
	v_frexp_mant_f32_e32 v6, v16
	v_cmp_gt_f32_e32 vcc, s18, v6
	s_mov_b32 s18, 0x3f317218
	s_addc_u32 s86, s5, 0
	v_cndmask_b32_e64 v7, 1.0, 2.0, vcc
	v_mul_f32_e32 v6, v6, v7
	v_add_f32_e32 v9, 1.0, v6
	v_rcp_f32_e32 v14, v9
	v_add_f32_e32 v7, -1.0, v9
	v_sub_f32_e32 v11, v6, v7
	v_add_f32_e32 v7, -1.0, v6
	v_mul_f32_e32 v15, v7, v14
	v_mul_f32_e32 v8, v9, v15
	v_fma_f32 v10, v15, v9, -v8
	v_fmac_f32_e32 v10, v15, v11
	v_add_f32_e32 v6, v8, v10
	v_sub_f32_e32 v9, v7, v6
	v_pk_add_f32 v[12:13], v[6:7], v[8:9] neg_lo:[0,1] neg_hi:[0,1]
	v_mov_b32_e32 v11, v6
	v_pk_add_f32 v[6:7], v[12:13], v[10:11] neg_lo:[0,1] neg_hi:[0,1]
	s_add_u32 s87, s4, 0x2c00000
	v_add_f32_e32 v6, v6, v7
	v_add_f32_e32 v6, v9, v6
	v_mul_f32_e32 v7, v14, v6
	v_add_f32_e32 v6, v15, v7
	v_sub_f32_e32 v8, v6, v15
	v_sub_f32_e32 v17, v7, v8
	v_mul_f32_e32 v7, v6, v6
	v_fma_f32 v9, v6, v6, -v7
	v_add_f32_e32 v8, v17, v17
	v_fmac_f32_e32 v9, v6, v8
	v_add_f32_e32 v8, v7, v9
	v_fmamk_f32 v10, v8, 0x3e76c4e1, v197
	v_fmaak_f32 v10, v8, v10, 0x3ecccdef
	v_sub_f32_e32 v7, v8, v7
	v_sub_f32_e32 v18, v9, v7
	v_mul_f32_e32 v7, v8, v10
	v_fma_f32 v9, v8, v10, -v7
	v_fmac_f32_e32 v9, v18, v10
	v_add_f32_e32 v10, v7, v9
	v_add_f32_e32 v11, 0x3f2aaaaa, v10
	v_sub_f32_e32 v7, v10, v7
	v_sub_f32_e32 v7, v9, v7
	v_add_f32_e32 v9, 0xbf2aaaaa, v11
	v_add_f32_e32 v7, 0x31739010, v7
	v_sub_f32_e32 v9, v10, v9
	v_pk_mul_f32 v[12:13], v[6:7], v[8:9]
	v_pk_add_f32 v[14:15], v[6:7], v[8:9]
	v_fma_f32 v10, v8, v6, -v12
	v_fmac_f32_e32 v10, v8, v17
	v_mov_b32_e32 v13, v15
	v_fmac_f32_e32 v10, v18, v6
	v_pk_add_f32 v[8:9], v[12:13], v[10:11]
	v_ldexp_f32 v18, v17, 1
	v_sub_f32_e32 v7, v8, v12
	v_sub_f32_e32 v7, v10, v7
	v_sub_f32_e32 v10, v11, v9
	v_add_f32_e32 v14, v15, v10
	v_pk_mul_f32 v[10:11], v[8:9], v[8:9] op_sel:[0,1] op_sel_hi:[1,0]
	v_cvt_f64_f32_e32 v[12:13], v16
	v_frexp_exp_i32_f64_e32 v11, v[12:13]
	v_subbrev_co_u32_e32 v11, vcc, 0, v11, vcc
	v_cvt_f32_i32_e32 v11, v11
	v_fma_f32 v12, v8, v9, -v10
	v_fmac_f32_e32 v12, v8, v14
	v_fmac_f32_e32 v12, v7, v9
	v_mul_f32_e32 v8, 0x3f317218, v11
	v_fma_f32 v14, v11, s18, -v8
	v_fmac_f32_e32 v14, 0xb102e308, v11
	v_ldexp_f32 v15, v6, 1
	v_add_f32_e32 v9, v10, v12
	v_pk_add_f32 v[6:7], v[8:9], v[14:15]
	v_mov_b32_e32 v16, v9
	v_mov_b32_e32 v17, v7
	v_mov_b32_e32 v11, v15
	v_pk_add_f32 v[10:11], v[16:17], v[10:11] neg_lo:[0,1] neg_hi:[0,1]
	v_mov_b32_e32 v13, v9
	v_pk_add_f32 v[10:11], v[12:13], v[10:11] neg_lo:[0,1] neg_hi:[0,1]
	v_mov_b32_e32 v15, v6
	v_add_f32_e32 v9, v18, v10
	v_add_f32_e32 v9, v9, v11
	v_pk_add_f32 v[10:11], v[6:7], v[8:9] neg_lo:[0,1] neg_hi:[0,1]
	v_pk_add_f32 v[12:13], v[6:7], v[8:9]
	v_mov_b32_e32 v8, v9
	v_mov_b32_e32 v11, v13
	v_pk_add_f32 v[16:17], v[14:15], v[10:11] neg_lo:[0,1] neg_hi:[0,1]
	v_pk_add_f32 v[10:11], v[14:15], v[10:11]
	v_mov_b32_e32 v9, v6
	v_pk_add_f32 v[14:15], v[10:11], v[6:7] op_sel:[1,0] op_sel_hi:[0,1] neg_lo:[0,1] neg_hi:[0,1]
	v_pk_add_f32 v[18:19], v[12:13], v[14:15] op_sel_hi:[1,0] neg_lo:[0,1] neg_hi:[0,1]
	v_mov_b32_e32 v12, v13
	v_mov_b32_e32 v13, v11
	v_pk_mov_b32 v[14:15], v[6:7], v[14:15] op_sel:[1,0]
	v_mov_b32_e32 v18, v16
	v_pk_add_f32 v[12:13], v[12:13], v[14:15] neg_lo:[0,1] neg_hi:[0,1]
	v_mov_b32_e32 v17, v11
	v_pk_add_f32 v[6:7], v[8:9], v[12:13] neg_lo:[0,1] neg_hi:[0,1]
	s_movk_i32 s18, 0x204
	v_pk_add_f32 v[8:9], v[18:19], v[6:7]
	s_addc_u32 s81, s5, 0
	v_pk_add_f32 v[12:13], v[8:9], v[8:9] op_sel:[0,1] op_sel_hi:[1,0]
	s_sub_i32 s97, s2, s78
	v_pk_add_f32 v[10:11], v[10:11], v[12:13] op_sel:[1,0] op_sel_hi:[0,1]
	v_mov_b32_e32 v9, v10
	v_pk_add_f32 v[14:15], v[8:9], v[16:17] neg_lo:[0,1] neg_hi:[0,1]
	v_mov_b32_e32 v7, v12
	v_sub_f32_e32 v8, v8, v14
	v_pk_add_f32 v[6:7], v[6:7], v[14:15] neg_lo:[0,1] neg_hi:[0,1]
	v_sub_f32_e32 v8, v16, v8
	v_add_f32_e32 v6, v6, v8
	v_add_f32_e32 v6, v6, v7
	v_add_f32_e32 v7, v10, v6
	v_sub_f32_e32 v8, v7, v10
	v_sub_f32_e32 v6, v6, v8
	v_mul_f32_e32 v8, v3, v7
	v_fma_f32 v7, v3, v7, -v8
	v_fmac_f32_e32 v7, v3, v6
	v_add_f32_e32 v6, v8, v7
	v_cmp_class_f32_e64 vcc, v8, s18
	v_sub_f32_e32 v9, v6, v8
	v_sub_f32_e32 v7, v7, v9
	v_cndmask_b32_e32 v6, v6, v8, vcc
	v_cmp_eq_f32_e32 vcc, s24, v6
	s_movk_i32 s2, 0x1ff
	v_add_u32_e32 v96, 0xa00, v80
	v_cndmask_b32_e32 v8, 0, v211, vcc
	v_sub_f32_e32 v9, v6, v8
	v_mul_f32_e32 v10, 0x3fb8aa3b, v9
	v_fma_f32 v11, v9, s22, -v10
	v_rndne_f32_e32 v12, v10
	v_fmac_f32_e32 v11, 0x32a5705f, v9
	v_sub_f32_e32 v10, v10, v12
	v_add_f32_e32 v10, v10, v11
	v_exp_f32_e32 v10, v10
	v_cvt_i32_f32_e32 v11, v12
	v_cmp_neq_f32_e64 vcc, |v6|, s3
	v_ashrrev_i32_e32 v131, 5, v80
	v_lshlrev_b32_e32 v2, 4, v80
	v_cndmask_b32_e32 v6, 0, v7, vcc
	v_ldexp_f32 v7, v10, v11
	v_cmp_ngt_f32_e32 vcc, s23, v9
	v_add_f32_e32 v6, v8, v6
	v_lshlrev_b32_e32 v5, 6, v131
	v_cndmask_b32_e32 v7, 0, v7, vcc
	v_cmp_nlt_f32_e32 vcc, s24, v9
	v_and_b32_e32 v2, 0x1f0, v2
	v_add_u32_e32 v20, 0, v2
	v_cndmask_b32_e32 v7, v209, v7, vcc
	v_fma_f32 v6, v7, v6, v7
	v_cmp_class_f32_e64 vcc, v7, s18
	v_and_b32_e32 v2, 63, v80
	v_ashrrev_i32_e32 v151, 6, v80
	v_cndmask_b32_e32 v6, v6, v7, vcc
	v_and_b32_e32 v7, 0x7fffffff, v6
	v_div_scale_f32 v8, s[18:19], v7, v7, 1.0
	v_rcp_f32_e32 v9, v8
	v_div_scale_f32 v7, vcc, 1.0, v7, 1.0
	v_cmp_gt_u32_e64 s[18:19], s38, v80
	v_fma_f32 v10, -v8, v9, 1.0
	v_fmac_f32_e32 v9, v10, v9
	v_mul_f32_e32 v10, v7, v9
	v_fma_f32 v11, -v8, v10, v7
	v_fmac_f32_e32 v10, v11, v9
	v_writelane_b32 v254, s18, 59
	v_fma_f32 v7, -v8, v10, v7
	v_div_fmas_f32 v7, v7, v9, v10
	v_writelane_b32 v254, s19, 60
	v_cmp_gt_u32_e64 s[18:19], s38, v88
	v_cmp_neq_f32_e32 vcc, s3, v3
	s_movk_i32 s3, 0xfbff
	v_writelane_b32 v254, s18, 61
	v_add_u32_e32 v3, 0x800, v80
	v_max_i32_e32 v9, 0x600, v80
	v_writelane_b32 v254, s19, 62
	v_cmp_lt_u32_e64 s[18:19], s3, v80
	s_movk_i32 s3, 0xfc00
	v_sub_u32_e32 v9, v9, v80
	v_writelane_b32 v254, s18, 51
	v_add_u32_e32 v9, 0x1ff, v9
	v_lshrrev_b32_e32 v11, 9, v9
	v_writelane_b32 v254, s19, 52
	v_cmp_gt_u32_e64 s[18:19], s38, v92
	v_add_u32_e32 v11, 1, v11
	v_and_b32_e32 v157, 0xfffffe, v11
	v_writelane_b32 v254, s18, 53
	v_lshlrev_b32_e32 v154, 1, v80
	s_movk_i32 s44, 0x104
	v_writelane_b32 v254, s19, 54
	v_cmp_gt_u32_e64 s[18:19], s38, v3
	v_bfi_b32 v3, s3, v3, v80
	v_add_u32_e32 v94, 0xfffffc00, v3
	v_add_u32_e32 v3, 0xc00, v80
	v_cmp_gt_u32_e64 s[30:31], s38, v3
	v_bfi_b32 v3, s3, v3, v80
	v_add_u32_e32 v98, 0xfffffc00, v3
	v_add_u32_e32 v3, 0x1000, v80
	v_cmp_gt_u32_e64 s[36:37], s38, v3
	v_bfi_b32 v3, s3, v3, v80
	v_cmp_lt_u32_e64 s[2:3], s2, v9
	v_writelane_b32 v254, s18, 45
	v_div_fixup_f32 v6, v7, |v6|, 1.0
	v_writelane_b32 v255, s2, 7
	v_writelane_b32 v254, s19, 46
	v_cmp_gt_u32_e64 s[18:19], s38, v96
	v_writelane_b32 v255, s3, 8
	v_cmp_ne_u32_e64 s[2:3], v11, v157
	v_writelane_b32 v254, s18, 47
	v_add_u32_e32 v100, 0xe00, v80
	v_writelane_b32 v255, s2, 9
	v_writelane_b32 v254, s19, 48
	v_add_u32_e32 v102, 0xfffffc00, v3
	v_writelane_b32 v255, s3, 10
	s_mov_b64 s[2:3], 0x629b000
	v_add_u32_e32 v3, 0x1200, v80
	v_lshl_add_u64 v[106:107], v[0:1], 0, s[2:3]
	v_mad_i64_i32 v[108:109], s[2:3], v5, s90, 0
	v_lshlrev_b32_e32 v82, 8, v80
	v_lshlrev_b32_e32 v129, 2, v80
	v_lshl_add_u32 v21, v2, 2, 0
	v_and_b32_e32 v4, 62, v154
	v_cndmask_b32_e32 v156, 0, v6, vcc
	v_and_b32_e32 v6, 0x3ff, v80
	v_add_u32_e32 v86, 0xfffffc00, v80
	v_and_b32_e32 v8, 0x3ff, v88
	v_add_u32_e32 v90, 0xfffffe00, v80
	v_and_b32_e32 v10, 0x3ff, v92
	v_and_b32_e32 v12, 0x3ff, v96
	v_and_b32_e32 v14, 0x3ff, v100
	v_cmp_gt_u32_e64 s[28:29], s38, v100
	v_and_b32_e32 v16, 0x3ff, v3
	v_cmp_gt_u32_e64 s[38:39], s38, v3
	v_mul_lo_u32 v3, v131, s96
	v_mul_lo_u32 v7, v151, s44
	v_and_b32_e32 v0, 31, v80
	v_readlane_b32 s2, v254, 32
	v_ashrrev_i32_e32 v83, 31, v82
	v_add_u32_e32 v130, 0, v129
	v_lshl_add_u32 v150, v131, 8, 0
	v_cmp_gt_i32_e64 s[16:17], 64, v80
	s_mov_b64 s[24:25], 0x90000
	s_mov_b64 s[22:23], 0x87000
	v_mad_u32_u24 v155, v4, s44, 0
	v_ashrrev_i32_e32 v87, 31, v86
	v_ashrrev_i32_e32 v91, 31, v90
	v_ashrrev_i32_e32 v89, 31, v88
	v_ashrrev_i32_e32 v95, 31, v94
	v_ashrrev_i32_e32 v93, 31, v92
	v_ashrrev_i32_e32 v99, 31, v98
	v_ashrrev_i32_e32 v97, 31, v96
	v_ashrrev_i32_e32 v103, 31, v102
	v_ashrrev_i32_e32 v101, 31, v100
	v_lshl_add_u32 v158, v157, 9, v80
	v_mov_b32_e32 v104, v80
	v_mov_b32_e32 v105, v88
	v_lshl_or_b32 v108, v0, 4, v108
	v_add_u32_e32 v159, s2, v129
	v_lshlrev_b32_e32 v160, 2, v131
	v_lshlrev_b32_e32 v161, 1, v131
	v_lshl_add_u32 v162, v131, 1, v131
	v_lshlrev_b32_e32 v110, 2, v6
	v_lshlrev_b32_e32 v112, 2, v8
	v_lshlrev_b32_e32 v114, 2, v10
	v_lshlrev_b32_e32 v116, 2, v12
	v_lshlrev_b32_e32 v118, 2, v14
	v_lshlrev_b32_e32 v120, 2, v16
	v_add_u32_e32 v163, v20, v3
	v_lshlrev_b32_e32 v122, 2, v2
	v_add_u32_e32 v164, v21, v7
	v_lshlrev_b32_e32 v124, 1, v4
	s_branch .LBB0_1125
.LBB0_1124:
	s_addk_i32 s79, 0x100
	s_cmp_ge_i32 s79, s80
	s_cbranch_scc1 .LBB0_1211
